# phase E: second-round (head-norm) items reassigned from the G3 blocks to the lightly loaded blocks
# speedup vs baseline: 1.0057x; 1.0038x over previous
.LBB0_135:
	s_cmpk_lt_i32 s27, 0x140
	s_cbranch_scc1 .LBB0_164
	s_cmpk_lt_i32 s27, 0x200
	s_cbranch_scc1 .Le_p192
	s_cmpk_lt_i32 s27, 0x278
	s_cbranch_scc1 .LBB0_164
	s_cmpk_gt_i32 s27, 0x2bf
	s_cbranch_scc1 .LBB0_164
	s_addk_i32 s27, 0x48
	s_cmpk_gt_i32 s27, 0x2ff
	s_cbranch_scc1 .LBB0_164
	s_branch .LBB0_136
.Le_p192:
	s_addk_i32 s27, 0xc0
